# attention main loop: drop s_nop 11 after MFMA-segment barrier; issue K/V ring DMA after first four PV MFMAs
# baseline (speedup 1.0000x reference)
; #define ATT_DMA(i, slot) do { if (ABL & 1) break; const long off_ = (long)ATT_TAU(i) * KVBLK * INW; \
;         glds16(ksrc + off_, (unsigned)__builtin_amdgcn_readfirstlane(kdst + (slot) * SLOTB)); glds16(vsrc + off_, (unsigned)__builtin_amdgcn_readfirstlane(vdst + (slot) * SLOTB)); } while (0)
; #define ATT_BARV(N) do { if (ABL & 16) asm volatile("s_waitcnt vmcnt(" #N ") lgkmcnt(0)\n\ts_nop 11" ::: "memory"); else asm volatile("s_waitcnt vmcnt(" #N ") lgkmcnt(0)\n\ts_barrier\n\ts_nop 11" ::: "memory"); } while (0)
; #define ATT_SB() __builtin_amdgcn_sched_barrier(0)
; #define ATT_LDQ() const bf16x8 qf0 = *(const __attribute__((address_space(3))) bf16x8*)(qp), qf1 = *(const __attribute__((address_space(3))) bf16x8*)(qp + 1024), qf2 = *(const __attribute__((address_space(3))) bf16x8*)(qp + 2048), qf3 = *(const __attribute__((address_space(3))) bf16x8*)(qp + 3072)
; #define ATT_KA(off) (*(const __attribute__((address_space(3))) bf16x8*)(kp + (off)))
; #define ATT_KB(off) (*(const __attribute__((address_space(3))) bf16x8*)(kp + koB + (off)))
; #define ATT_VFR(n, ks) const s16x4 l0##n = vtr(vp + (ks) * 1024), h0##n = vtr(vp + (ks) * 1024 + 512), l1##n = vtr(vp + 4096 + (ks) * 1024), h1##n = vtr(vp + 4096 + (ks) * 1024 + 512)
;     ...
;     for (int i = 1; i < NTe; ++i) {
;         const int tau = ATT_TAU(i), slot = i & 3;
;         { const int id_ = i + 2 < NTe ? i + 2 : NTe - 1; ATT_DMA(id_, (i + 2) & 3); }
;         { const lds_cptr vp = vp0 + ((i - 1) & 3) * SLOTB, kp = kp0 + slot * SLOTB;
;           ATT_VFR(a, 0); ATT_VFR(b, 1);
;           const bf16x8 ka0 = ATT_KA(0), ka1 = ATT_KA(2048), ka2 = ATT_KB(0), ka3 = ATT_KB(2048);
;           ATT_SB();
;           ATT_PVK(a, pa0, pb0); ATT_SB();
;           ATT_VFR(c, 2); ATT_SB();
;           ATT_PVK(b, pa1, pb1); ATT_SB();
;           ATT_VFR(d, 3);
;           const bf16x8 kb0 = ATT_KA(4096), kb1 = ATT_KA(6144), kb2 = ATT_KB(4096), kb3 = ATT_KB(6144);
;           ATT_LDQ();
;           ATT_SB();
;           ATT_PVK(c, pa2, pb2); ATT_SB();
;           ATT_PVK(d, pa3, pb3); ATT_SB();
;           ATT_QKA(); ATT_QKB(); }
;         ATT_SB();
;         ATT_BARV(2);
;         __builtin_amdgcn_s_setprio(1);
;         ATT_SB();
;         { const bool diag = tau == td; const float dq = (float)(tq - tau * KVBLK);
.LBB0_339:
	s_add_i32 s30, s15, s28
	s_cmp_lt_i32 s28, s19
	s_cselect_b32 s30, s30, s27
	s_add_i32 s31, s28, 2
	s_cmp_lt_i32 s31, s20
	s_cselect_b32 s34, s31, s23
	s_add_i32 s35, s34, s15
	s_sub_i32 s36, s22, s34
	s_cmp_lt_i32 s34, s19
	s_cselect_b32 s36, s35, s36
	s_add_i32 s34, s29, 0xffffa000
	s_and_b32 s35, s29, 0x6000
	v_add_u32_e32 v112, s35, v191
	s_and_b32 s34, s34, 0x6000
	v_add_u32_e32 v197, s34, v181
	ds_read_b64_tr_b16 v[92:93], v112 offset:32768
	ds_read_b64_tr_b16 v[94:95], v112 offset:33280
	ds_read_b64_tr_b16 v[96:97], v112 offset:33792
	ds_read_b64_tr_b16 v[98:99], v112 offset:34304
	ds_read_b64_tr_b16 v[104:105], v112 offset:36864
	ds_read_b64_tr_b16 v[106:107], v112 offset:37376
	ds_read_b64_tr_b16 v[108:109], v112 offset:37888
	ds_read_b64_tr_b16 v[110:111], v112 offset:38400
	ds_read_b128 v[158:161], v197
	ds_read_b128 v[192:195], v197 offset:2048
	v_add_u32_e32 v196, v197, v183
	ds_read_b128 v[198:201], v196
	ds_read_b128 v[202:205], v196 offset:2048
	s_waitcnt lgkmcnt(10)
	v_mfma_f32_32x32x16_bf16 v[48:63], v[88:91], v[92:95], v[48:63]
	s_waitcnt lgkmcnt(6)
	v_mfma_f32_32x32x16_bf16 v[32:47], v[88:91], v[104:107], v[32:47]
	v_mfma_f32_32x32x16_bf16 v[16:31], v[100:103], v[92:95], v[16:31]
	v_mfma_f32_32x32x16_bf16 v[0:15], v[100:103], v[104:107], v[0:15]
	v_mad_i64_i32 v[92:93], s[34:35], s36, v224, v[148:149]
	s_add_i32 s34, s29, 0xffffe000
	s_and_b32 s37, s34, 0x6000
	s_add_i32 s34, s37, s45
	s_mov_b32 s35, m0
	s_mov_b32 m0, s34
	s_nop 0
	global_load_lds_dwordx4 v[92:93], off
	s_mov_b32 m0, s35
	s_nop 0
	v_mad_i64_i32 v[92:93], s[34:35], s36, v224, v[146:147]
	s_add_i32 s34, s37, s18
	s_mov_b32 s35, m0
	s_mov_b32 m0, s34
	s_nop 0
	global_load_lds_dwordx4 v[92:93], off
	s_mov_b32 m0, s35
	ds_read_b64_tr_b16 v[88:89], v112 offset:34816
	ds_read_b64_tr_b16 v[90:91], v112 offset:35328
	ds_read_b64_tr_b16 v[92:93], v112 offset:38912
	ds_read_b64_tr_b16 v[94:95], v112 offset:39424
	v_mfma_f32_32x32x16_bf16 v[48:63], v[76:79], v[96:99], v[48:63]
	s_waitcnt lgkmcnt(8)
	v_mfma_f32_32x32x16_bf16 v[32:47], v[76:79], v[108:111], v[32:47]
	v_mfma_f32_32x32x16_bf16 v[16:31], v[84:87], v[96:99], v[16:31]
	v_mfma_f32_32x32x16_bf16 v[0:15], v[84:87], v[108:111], v[0:15]
	ds_read_b64_tr_b16 v[76:77], v112 offset:35840
	ds_read_b64_tr_b16 v[78:79], v112 offset:36352
	ds_read_b64_tr_b16 v[84:85], v112 offset:39936
	ds_read_b64_tr_b16 v[86:87], v112 offset:40448
	ds_read_b128 v[206:209], v197 offset:4096
	ds_read_b128 v[228:231], v197 offset:6144
	ds_read_b128 v[232:235], v196 offset:4096
	ds_read_b128 v[236:239], v196 offset:6144
	ds_read_b128 v[240:243], v174
	ds_read_b128 v[244:247], v174 offset:1024
	ds_read_b128 v[248:251], v174 offset:2048
	ds_read_b128 v[186:189], v174 offset:3072
	s_waitcnt lgkmcnt(14)
	v_mfma_f32_32x32x16_bf16 v[48:63], v[72:75], v[88:91], v[48:63]
	s_waitcnt lgkmcnt(12)
	v_mfma_f32_32x32x16_bf16 v[32:47], v[72:75], v[92:95], v[32:47]
	v_mfma_f32_32x32x16_bf16 v[16:31], v[80:83], v[88:91], v[16:31]
	v_mfma_f32_32x32x16_bf16 v[0:15], v[80:83], v[92:95], v[0:15]
	s_waitcnt lgkmcnt(10)
	v_mfma_f32_32x32x16_bf16 v[48:63], v[68:71], v[76:79], v[48:63]
	s_waitcnt lgkmcnt(8)
	v_mfma_f32_32x32x16_bf16 v[32:47], v[68:71], v[84:87], v[32:47]
	v_mfma_f32_32x32x16_bf16 v[16:31], v[64:67], v[76:79], v[16:31]
	v_mfma_f32_32x32x16_bf16 v[0:15], v[64:67], v[84:87], v[0:15]
	v_mfma_f32_32x32x16_bf16 v[112:127], v[134:137], v[142:145], 0
	v_mfma_f32_32x32x16_bf16 v[96:111], v[130:133], v[142:145], 0
	v_mfma_f32_32x32x16_bf16 v[80:95], v[134:137], v[138:141], 0
	v_mfma_f32_32x32x16_bf16 v[64:79], v[130:133], v[138:141], 0
	s_waitcnt lgkmcnt(3)
	v_mfma_f32_32x32x16_bf16 v[112:127], v[158:161], v[240:243], v[112:127]
	v_mfma_f32_32x32x16_bf16 v[96:111], v[192:195], v[240:243], v[96:111]
	s_waitcnt lgkmcnt(1)
	v_mfma_f32_32x32x16_bf16 v[80:95], v[206:209], v[248:251], v[80:95]
	v_mfma_f32_32x32x16_bf16 v[64:79], v[228:231], v[248:251], v[64:79]
	v_mfma_f32_32x32x16_bf16 v[112:127], v[198:201], v[244:247], v[112:127]
	v_mfma_f32_32x32x16_bf16 v[96:111], v[202:205], v[244:247], v[96:111]
	s_waitcnt lgkmcnt(0)
	v_mfma_f32_32x32x16_bf16 v[80:95], v[232:235], v[186:189], v[80:95]
	v_mfma_f32_32x32x16_bf16 v[64:79], v[236:239], v[186:189], v[64:79]
	s_waitcnt vmcnt(2) lgkmcnt(0)
	s_barrier
	s_setprio 1
	s_cmp_eq_u32 s30, s21
	s_cselect_b64 s[42:43], -1, 0
	s_lshl_b32 s34, s30, 6
	v_subrev_u32_e32 v128, s34, v171
	v_cvt_f32_i32_e32 v199, v128
	s_cmp_lg_u32 s30, s21
	s_cbranch_scc1 .LBB0_341
; #define ATT_DIAG_BIAS(s0, s1) do { const float dqh_ = dq - (float)(4 * hi); _Pragma("unroll") for (int r = 0; r < 16; ++r) { const float c_ = (float)((r & 3) + 8 * (r >> 2)); \
;         s0[r] = __builtin_fmaf(-sl, __builtin_fabsf(dqh_ - c_), s0[r]); s1[r] = __builtin_fmaf(-sl, __builtin_fabsf(dqh_ - (c_ + 32.f)), s1[r]); } } while (0)
;     ...
;           if (diag) { ATT_DIAG_BIAS(sa0, sa1); ATT_DIAG_BIAS(sb0, sb1); }
	s_mov_b32 s34, 0xc2000000
	v_sub_f32_e32 v128, v199, v184
	s_mov_b32 s35, 0xc2040000
	v_pk_add_f32 v[158:159], v[128:129], s[34:35] op_sel_hi:[0,1]
	s_mov_b32 s34, -2.0
	s_mov_b32 s35, 0xc0400000
	v_pk_add_f32 v[160:161], v[128:129], s[34:35] op_sel_hi:[0,1]
	s_mov_b32 s34, 0xc2080000
	s_mov_b32 s35, 0xc20c0000
	v_pk_add_f32 v[162:163], v[128:129], s[34:35] op_sel_hi:[0,1]
	s_mov_b32 s34, 0xc1000000
	s_mov_b32 s35, 0xc1100000
	v_pk_add_f32 v[186:187], v[128:129], s[34:35] op_sel_hi:[0,1]
	s_mov_b32 s34, 0xc2200000
	s_mov_b32 s35, 0xc2240000
	v_pk_add_f32 v[188:189], v[128:129], s[34:35] op_sel_hi:[0,1]
	s_mov_b32 s34, 0xc1200000
	s_mov_b32 s35, 0xc1300000
	v_pk_add_f32 v[192:193], v[128:129], s[34:35] op_sel_hi:[0,1]
	s_mov_b32 s34, 0xc2280000
	s_mov_b32 s35, 0xc22c0000
	v_pk_add_f32 v[194:195], v[128:129], s[34:35] op_sel_hi:[0,1]
	s_mov_b32 s34, 0xc1800000
	s_mov_b32 s35, 0xc1880000
	v_pk_add_f32 v[200:201], v[128:129], s[34:35] op_sel_hi:[0,1]
	s_mov_b32 s34, 0xc2400000
	s_mov_b32 s35, 0xc2440000
	v_pk_add_f32 v[202:203], v[128:129], s[34:35] op_sel_hi:[0,1]
	s_mov_b32 s34, 0xc1900000
	s_mov_b32 s35, 0xc1980000
	v_pk_add_f32 v[204:205], v[128:129], s[34:35] op_sel_hi:[0,1]
	s_mov_b32 s34, 0xc2480000
	s_mov_b32 s35, 0xc24c0000
	v_pk_add_f32 v[206:207], v[128:129], s[34:35] op_sel_hi:[0,1]
	s_mov_b32 s34, 0xc1c00000
	s_mov_b32 s35, 0xc1c80000
	v_pk_add_f32 v[208:209], v[128:129], s[34:35] op_sel_hi:[0,1]
	s_mov_b32 s34, 0xc2600000
	s_mov_b32 s35, 0xc2640000
	v_pk_add_f32 v[210:211], v[128:129], s[34:35] op_sel_hi:[0,1]
	s_mov_b32 s34, 0xc1d00000
	s_mov_b32 s35, 0xc1d80000
	v_pk_add_f32 v[214:215], v[128:129], s[34:35] op_sel_hi:[0,1]
	s_mov_b32 s34, 0xc2680000
	s_mov_b32 s35, 0xc26c0000
	v_add_f32_e32 v155, -1.0, v128
	v_pk_add_f32 v[222:223], v[128:129], s[34:35] op_sel_hi:[0,1]
	v_and_b32_e32 v159, 0x7fffffff, v159
	v_and_b32_e32 v158, 0x7fffffff, v158
	v_and_b32_e32 v163, 0x7fffffff, v163
	v_and_b32_e32 v162, 0x7fffffff, v162
	v_and_b32_e32 v187, 0x7fffffff, v187
	v_and_b32_e32 v186, 0x7fffffff, v186
	v_and_b32_e32 v189, 0x7fffffff, v189
	v_and_b32_e32 v188, 0x7fffffff, v188
	v_and_b32_e32 v193, 0x7fffffff, v193
	v_and_b32_e32 v192, 0x7fffffff, v192
	v_and_b32_e32 v195, 0x7fffffff, v195
	v_and_b32_e32 v194, 0x7fffffff, v194
	v_and_b32_e32 v201, 0x7fffffff, v201
	v_and_b32_e32 v200, 0x7fffffff, v200
	v_and_b32_e32 v203, 0x7fffffff, v203
	v_and_b32_e32 v202, 0x7fffffff, v202
	v_and_b32_e32 v205, 0x7fffffff, v205
	v_and_b32_e32 v204, 0x7fffffff, v204
	v_and_b32_e32 v207, 0x7fffffff, v207
	v_and_b32_e32 v206, 0x7fffffff, v206
	v_and_b32_e32 v209, 0x7fffffff, v209
	v_and_b32_e32 v208, 0x7fffffff, v208
	v_and_b32_e32 v211, 0x7fffffff, v211
	v_and_b32_e32 v210, 0x7fffffff, v210
	v_and_b32_e32 v215, 0x7fffffff, v215
	v_and_b32_e32 v214, 0x7fffffff, v214
	v_and_b32_e32 v223, 0x7fffffff, v223
	v_and_b32_e32 v222, 0x7fffffff, v222
	v_and_b32_e32 v161, 0x7fffffff, v161
	v_and_b32_e32 v160, 0x7fffffff, v160
	v_and_b32_e32 v228, 0x7fffffff, v128
	v_and_b32_e32 v229, 0x7fffffff, v155
	v_mov_b32_e32 v155, v154
	v_pk_fma_f32 v[94:95], v[154:155], v[214:215], v[94:95]
	v_pk_fma_f32 v[92:93], v[154:155], v[208:209], v[92:93]
	v_pk_fma_f32 v[90:91], v[154:155], v[204:205], v[90:91]
	v_pk_fma_f32 v[88:89], v[154:155], v[200:201], v[88:89]
	v_pk_fma_f32 v[86:87], v[154:155], v[192:193], v[86:87]
	v_pk_fma_f32 v[84:85], v[154:155], v[186:187], v[84:85]
	v_pk_fma_f32 v[82:83], v[154:155], v[160:161], v[82:83]
	v_pk_fma_f32 v[80:81], v[156:157], v[228:229], v[80:81]
	v_pk_fma_f32 v[78:79], v[154:155], v[222:223], v[78:79]
	v_pk_fma_f32 v[76:77], v[154:155], v[210:211], v[76:77]
	v_pk_fma_f32 v[74:75], v[154:155], v[206:207], v[74:75]
	v_pk_fma_f32 v[72:73], v[154:155], v[202:203], v[72:73]
	v_pk_fma_f32 v[70:71], v[154:155], v[194:195], v[70:71]
	v_pk_fma_f32 v[68:69], v[154:155], v[188:189], v[68:69]
	v_pk_fma_f32 v[66:67], v[154:155], v[162:163], v[66:67]
	v_pk_fma_f32 v[64:65], v[156:157], v[158:159], v[64:65]
	v_pk_fma_f32 v[126:127], v[154:155], v[214:215], v[126:127]
	v_pk_fma_f32 v[124:125], v[154:155], v[208:209], v[124:125]
	v_pk_fma_f32 v[122:123], v[154:155], v[204:205], v[122:123]
	v_pk_fma_f32 v[120:121], v[154:155], v[200:201], v[120:121]
	v_pk_fma_f32 v[118:119], v[154:155], v[192:193], v[118:119]
	v_pk_fma_f32 v[116:117], v[154:155], v[186:187], v[116:117]
	v_pk_fma_f32 v[114:115], v[154:155], v[160:161], v[114:115]
	v_pk_fma_f32 v[112:113], v[156:157], v[228:229], v[112:113]
	v_pk_fma_f32 v[110:111], v[154:155], v[222:223], v[110:111]
	v_pk_fma_f32 v[108:109], v[154:155], v[210:211], v[108:109]
	v_pk_fma_f32 v[106:107], v[154:155], v[206:207], v[106:107]
	v_pk_fma_f32 v[104:105], v[154:155], v[202:203], v[104:105]
	v_pk_fma_f32 v[102:103], v[154:155], v[194:195], v[102:103]
	v_pk_fma_f32 v[100:101], v[154:155], v[188:189], v[100:101]
	v_pk_fma_f32 v[98:99], v[154:155], v[162:163], v[98:99]
	v_pk_fma_f32 v[96:97], v[156:157], v[158:159], v[96:97]
